# sample recurrence: next item 64KB state block prefetched into idle VGPRs before the token loop; item top copies registers to LDS without waiting
# baseline (speedup 1.0000x reference)
; #define LAS __attribute__((address_space(3)))
; __device__ __forceinline__ void gdn_sample_item(LAS unsigned char* lds, int item, const bf16_t* qkv, const float* bg, const float* gconv_w, const float* st_gconv, const float* st_grec, bf16_t* zb, const float* gnorm_w, float* srec) {
;     ...
;     const float* S0 = st_grec + ((size_t)sb * NH + h) * DK * DV;
; #pragma unroll
;     for (int rr = 0; rr < 8; ++rr) { const int dk = (tid >> 5) + 16 * rr, c4 = 4 * (tid & 31); *(LAS f32x4*)(Sst + dk * 132 + c4) = __builtin_nontemporal_load((const f32x4*)(S0 + (size_t)dk * DV + c4)); }
; __device__ __forceinline__ void gdn_all(LAS unsigned char* lds, const XcdBarrier& xbar, const int G, const int bx, unsigned char* ws, float* out, const bf16_t* qkv, const float* bg, const float* gconv_w, ...
;     ...
;         if (bx < 64) { const int cw = nfull * G / 8 - (bx >> 3) * NCHUNK;
;             gdn_scan(lds, bx, 0, rec_of, gtarr, zb, gnorm_w, out + O_PREC + (size_t)bx * DK * DV, late_cnt, (unsigned)nlate, nlate > 0 ? (cw < 0 ? 0 : cw) : NCHUNK + 1); }
;         else for (int it = bx - 64; it < DECB * NH; it += G - 64) gdn_sample_item(lds, it, qkv, bg, gconv_w, st_gconv, st_grec, zb, gnorm_w, out + O_SREC);
.LBB0_704:
	s_cmp_gt_i32 s94, 63
	s_mov_b64 s[0:1], -1
	v_writelane_b32 v245, s52, 36
	s_cbranch_scc0 .LBB0_738
	s_mov_b32 s59, s53
	s_cmpk_gt_u32 s94, 0x43f
	s_cbranch_scc1 .LBB0_737
	v_readlane_b32 s36, v245, 19
	s_sub_i32 s22, s94, 64
	v_readlane_b32 s48, v245, 31
	v_readlane_b32 s49, v245, 32
	s_add_u32 s23, s48, 0x4df0000
	s_addc_u32 s24, s49, 0
	s_sub_i32 s25, s96, 64
	s_mov_b32 s1, 0
	s_waitcnt vmcnt(0)
	v_mov_b32_e32 v19, 0
	s_movk_i32 s26, 0x3000
	s_movk_i32 s27, 0x1800
	s_mov_b32 s28, 0x800000
	s_add_i32 s29, 0, 0x4000
	v_mbcnt_hi_u32_b32 v1, -1, v220
	v_mov_b32_e32 v72, 0x358637bd
	v_mov_b32_e32 v73, 0x2000
	v_mov_b32_e32 v74, 0x1000
	v_readlane_b32 s37, v245, 20
	v_readlane_b32 s38, v245, 21
	v_readlane_b32 s39, v245, 22
	v_readlane_b32 s40, v245, 23
	v_readlane_b32 s41, v245, 24
	v_readlane_b32 s42, v245, 25
	v_readlane_b32 s43, v245, 26
	v_readlane_b32 s44, v245, 27
	v_readlane_b32 s45, v245, 28
	v_readlane_b32 s46, v245, 29
	v_readlane_b32 s47, v245, 30
	v_readlane_b32 s50, v245, 33
	v_readlane_b32 s51, v245, 34
	s_mov_b32 s98, s22
	s_ashr_i32 s100, s98, 3
	s_and_b32 s98, s98, 7
	s_mov_b32 s101, 0
	s_lshl_b64 s[100:101], s[100:101], 17
	s_lshl_b32 s98, s98, 14
	s_or_b32 s100, s100, s98
	s_lshl_b64 s[100:101], s[100:101], 2
	v_readlane_b32 s98, v245, 9
	v_readlane_b32 s99, v245, 10
	v_lshlrev_b32_e32 v106, 2, v0
	v_and_b32_e32 v106, 0x7c, v106
	v_lshlrev_b32_e32 v106, 2, v106
	v_lshrrev_b32_e32 v107, 5, v0
	v_lshl_add_u32 v106, v107, 12, v106
	s_add_u32 s100, s98, s100
	s_addc_u32 s101, s99, s101
	global_load_dwordx4 v[112:115], v106, s[100:101] nt
	global_load_dwordx4 v[116:119], v106, s[100:101] offset:512 nt
	global_load_dwordx4 v[120:123], v106, s[100:101] offset:1024 nt
	global_load_dwordx4 v[124:127], v106, s[100:101] offset:1536 nt
	global_load_dwordx4 v[128:131], v106, s[100:101] offset:2048 nt
	global_load_dwordx4 v[136:139], v106, s[100:101] offset:2560 nt
	global_load_dwordx4 v[140:143], v106, s[100:101] offset:3072 nt
	global_load_dwordx4 v[144:147], v106, s[100:101] offset:3584 nt
	s_waitcnt vmcnt(0)
	s_branch .LBB0_708

; #define LAS __attribute__((address_space(3)))
; __device__ __forceinline__ void gdn_sample_item(LAS unsigned char* lds, int item, const bf16_t* qkv, const float* bg, const float* gconv_w, const float* st_gconv, const float* st_grec, bf16_t* zb, const float* gnorm_w, float* srec) {
;     ...
;     const float* S0 = st_grec + ((size_t)sb * NH + h) * DK * DV;
; #pragma unroll
;     for (int rr = 0; rr < 8; ++rr) { const int dk = (tid >> 5) + 16 * rr, c4 = 4 * (tid & 31); *(LAS f32x4*)(Sst + dk * 132 + c4) = __builtin_nontemporal_load((const f32x4*)(S0 + (size_t)dk * DV + c4)); }
.LBB0_708:
	s_ashr_i32 s8, s22, 3
	s_and_b32 s30, s22, 7
	s_ashr_i32 s9, s8, 31
	s_lshl_b64 s[4:5], s[8:9], 17
	s_lshl_b32 s0, s30, 14
	v_mov_b32_e32 v77, v0
	s_or_b32 s4, s4, s0
	v_readlane_b32 s40, v245, 3
	s_and_b32 s37, s22, -8
	s_lshl_b64 s[4:5], s[4:5], 2
	v_readlane_b32 s46, v245, 9
	v_lshlrev_b32_e32 v2, 2, v77
	v_readlane_b32 s47, v245, 10
	s_add_u32 s6, s46, s4
	v_ashrrev_i32_e32 v52, 5, v77
	v_and_b32_e32 v2, 0x7c, v2
	s_addc_u32 s7, s47, s5
	v_lshlrev_b32_e32 v18, 2, v2
	v_ashrrev_i32_e32 v53, 31, v52
	v_lshl_add_u64 v[44:45], s[6:7], 0, v[18:19]
	v_lshlrev_b64 v[20:21], 12, v[52:53]
	s_mov_b64 s[6:7], 0x200
	v_lshl_add_u64 v[22:23], v[20:21], 0, s[6:7]
	s_mov_b64 s[6:7], 0x400
	v_lshl_add_u64 v[24:25], v[20:21], 0, s[6:7]
	s_mov_b64 s[6:7], 0x600
	v_lshl_add_u64 v[26:27], v[20:21], 0, s[6:7]
	s_mov_b64 s[6:7], 0x800
	v_lshl_add_u64 v[28:29], v[20:21], 0, s[6:7]
	s_mov_b64 s[6:7], 0xa00
	v_lshl_add_u64 v[2:3], v[44:45], 0, v[20:21]
	v_lshl_add_u64 v[6:7], v[44:45], 0, v[22:23]
	v_lshl_add_u64 v[10:11], v[44:45], 0, v[24:25]
	v_lshl_add_u64 v[14:15], v[44:45], 0, v[26:27]
	v_lshl_add_u64 v[32:33], v[44:45], 0, v[28:29]
	v_lshl_add_u64 v[30:31], v[20:21], 0, s[6:7]
	s_mov_b64 s[6:7], 0xc00
	s_nop 0
	s_nop 0
	s_nop 0
	v_lshl_add_u64 v[34:35], v[44:45], 0, v[30:31]
	v_lshl_add_u64 v[32:33], v[20:21], 0, s[6:7]
	s_mov_b64 s[6:7], 0xe00
	v_lshl_add_u64 v[34:35], v[20:21], 0, s[6:7]
	v_lshl_add_u64 v[46:47], v[44:45], 0, v[32:33]
	v_lshl_add_u64 v[48:49], v[44:45], 0, v[34:35]
	s_nop 0
	s_movk_i32 s0, 0x1080
	v_and_b32_e32 v90, 7, v52
	v_lshlrev_b32_e32 v90, 4, v90
	v_mul_lo_u32 v52, v52, s0
	s_movk_i32 s6, 0x300
	v_add_u32_e32 v53, 0x6300, v52
	v_xor_b32_e32 v54, v90, v18
	v_readfirstlane_b32 s34, v77
	v_add_u32_e32 v76, v54, v52
	v_add_u32_e32 v75, v54, v53
	s_add_i32 s31, s37, 0x4080
	v_cmp_gt_i32_e32 vcc, s6, v77
	v_readlane_b32 s41, v245, 4
	v_readlane_b32 s42, v245, 5
	v_readlane_b32 s43, v245, 6
	v_readlane_b32 s44, v245, 7
	v_readlane_b32 s45, v245, 8
	v_readlane_b32 s48, v245, 11
	v_readlane_b32 s49, v245, 12
	v_readlane_b32 s50, v245, 13
	v_readlane_b32 s51, v245, 14
	v_readlane_b32 s52, v245, 15
	v_readlane_b32 s53, v245, 16
	v_readlane_b32 s54, v245, 17
	v_readlane_b32 s55, v245, 18
	ds_write_b128 v76, v[112:115] offset:16512
	ds_write_b128 v76, v[116:119] offset:17040
	ds_write_b128 v76, v[120:123] offset:17568
	ds_write_b128 v76, v[124:127] offset:18096
	ds_write_b128 v76, v[128:131] offset:18624
	ds_write_b128 v76, v[136:139] offset:19152
	ds_write_b128 v76, v[140:143] offset:19680
	ds_write_b128 v76, v[144:147] offset:20208
	s_and_saveexec_b64 s[6:7], vcc
	s_cbranch_execz .LBB0_723
	s_lshl_b32 s0, s30, 7
	s_mul_hi_i32 s9, s8, 3
	s_mul_i32 s8, s8, 3
	s_add_i32 s35, s37, 0x407d
	s_add_i32 s36, s37, 0x407e
	s_addk_i32 s37, 0x407f
	s_mov_b64 s[18:19], 0
	v_mov_b32_e32 v12, v77
	s_branch .LBB0_711

; #define LAS __attribute__((address_space(3)))
; __device__ __forceinline__ void gdn_sample_item(LAS unsigned char* lds, int item, const bf16_t* qkv, const float* bg, const float* gconv_w, const float* st_gconv, const float* st_grec, bf16_t* zb, const float* gnorm_w, float* srec) {
;     ...
;     const float* S0 = st_grec + ((size_t)sb * NH + h) * DK * DV;
; #pragma unroll
;     for (int rr = 0; rr < 8; ++rr) { const int dk = (tid >> 5) + 16 * rr, c4 = 4 * (tid & 31); *(LAS f32x4*)(Sst + dk * 132 + c4) = __builtin_nontemporal_load((const f32x4*)(S0 + (size_t)dk * DV + c4)); }
;     ...
;     float Sr[4][8];
; #pragma unroll
;     for (int cc = 0; cc < 4; ++cc)
; #pragma unroll
;         for (int j = 0; j < 8; ++j) Sr[cc][j] = Sst[(8 * dki + j) * 132 + cq + 32 * cc];
;     __syncthreads();
.LBB0_727:
	s_or_b64 exec, exec, s[6:7]
	v_lshlrev_b32_e32 v3, 2, v3
	v_and_b32_e32 v90, 7, v2
	v_lshlrev_b32_e32 v90, 4, v90
	v_xor_b32_e32 v78, v90, v3
	s_movk_i32 s0, 0x1080
	v_mad_u32_u24 v50, v2, s0, v78
	v_add_u32_e32 v12, 0x4000, v50
	v_add_u32_e32 v14, 0x4400, v50
	v_add_u32_e32 v16, 0x4800, v50
	v_add_u32_e32 v51, 0x4c00, v50
	v_add_u32_e32 v15, 0x4200, v50
	v_add_u32_e32 v17, 0x4600, v50
	v_add_u32_e32 v48, 0x4a00, v50
	v_add_u32_e32 v50, 0x4e00, v50
	ds_read2_b32 v[4:5], v12 offset0:32 offset1:64
	ds_read2_b32 v[36:37], v12 offset0:164 offset1:196
	ds_read2_b32 v[6:7], v14 offset0:40 offset1:72
	ds_read2_b32 v[38:39], v14 offset0:172 offset1:204
	ds_read2_b32 v[8:9], v16 offset0:48 offset1:80
	ds_read2_b32 v[40:41], v16 offset0:180 offset1:212
	ds_read2_b32 v[10:11], v51 offset0:56 offset1:88
	ds_read2_b32 v[44:45], v51 offset0:188 offset1:220
	ds_read2_b32 v[12:13], v12 offset0:96 offset1:128
	ds_read2_b32 v[42:43], v15 offset0:100 offset1:132
	ds_read2_b32 v[14:15], v14 offset0:104 offset1:136
	ds_read2_b32 v[46:47], v17 offset0:108 offset1:140
	ds_read2_b32 v[16:17], v16 offset0:112 offset1:144
	ds_read2_b32 v[48:49], v48 offset0:116 offset1:148
	ds_read2_b32 v[68:69], v51 offset0:120 offset1:152
	ds_read2_b32 v[50:51], v50 offset0:124 offset1:156
	s_add_i32 s6, 0, 0x2000
	v_mul_u32_u24_e32 v79, 0x1080, v2
	v_lshl_add_u32 v80, v2, 5, 0
	s_mov_b32 s0, 0
	v_cmp_eq_u32_e32 vcc, 0, v2
	v_add_u32_e32 v81, s6, v3
	s_mov_b32 s8, s29
	s_waitcnt lgkmcnt(9)
	v_mov_b32_e32 v64, v10
	s_waitcnt lgkmcnt(8)
	v_mov_b32_e32 v65, v44
	v_mov_b32_e32 v58, v8
	v_mov_b32_e32 v59, v40
	v_mov_b32_e32 v54, v6
	v_mov_b32_e32 v55, v38
	v_mov_b32_e32 v52, v4
	v_mov_b32_e32 v53, v36
	v_mov_b32_e32 v44, v11
	v_mov_b32_e32 v40, v9
	v_mov_b32_e32 v38, v7
	v_mov_b32_e32 v36, v5
	s_waitcnt lgkmcnt(1)
	v_mov_b32_e32 v56, v68
	s_waitcnt lgkmcnt(0)
	v_mov_b32_e32 v57, v50
	v_mov_b32_e32 v60, v16
	v_mov_b32_e32 v61, v48
	v_mov_b32_e32 v62, v14
	v_mov_b32_e32 v63, v46
	v_mov_b32_e32 v66, v12
	v_mov_b32_e32 v67, v42
	v_mov_b32_e32 v50, v69
	v_mov_b32_e32 v48, v17
	v_mov_b32_e32 v46, v15
	v_mov_b32_e32 v42, v13
	s_add_i32 s98, s22, s25
	s_cmpk_lt_i32 s98, 0x400
	s_cselect_b32 s98, s98, s22
	s_ashr_i32 s100, s98, 3
	s_and_b32 s98, s98, 7
	s_mov_b32 s101, 0
	s_lshl_b64 s[100:101], s[100:101], 17
	s_lshl_b32 s98, s98, 14
	s_or_b32 s100, s100, s98
	s_lshl_b64 s[100:101], s[100:101], 2
	v_readlane_b32 s98, v245, 9
	v_readlane_b32 s99, v245, 10
	v_lshlrev_b32_e32 v106, 2, v0
	v_and_b32_e32 v106, 0x7c, v106
	v_lshlrev_b32_e32 v106, 2, v106
	v_lshrrev_b32_e32 v107, 5, v0
	v_lshl_add_u32 v106, v107, 12, v106
	s_add_u32 s100, s98, s100
	s_addc_u32 s101, s99, s101
	global_load_dwordx4 v[112:115], v106, s[100:101] nt
	global_load_dwordx4 v[116:119], v106, s[100:101] offset:512 nt
	global_load_dwordx4 v[120:123], v106, s[100:101] offset:1024 nt
	global_load_dwordx4 v[124:127], v106, s[100:101] offset:1536 nt
	global_load_dwordx4 v[128:131], v106, s[100:101] offset:2048 nt
	global_load_dwordx4 v[136:139], v106, s[100:101] offset:2560 nt
	global_load_dwordx4 v[140:143], v106, s[100:101] offset:3072 nt
	global_load_dwordx4 v[144:147], v106, s[100:101] offset:3584 nt
	s_barrier
	s_branch .LBB0_729
